# v13: v12 plus the two small W2 compress GEMMs (k and v) on different workgroups, guarded by gridDim
# speedup vs baseline: 1.0049x; 1.0025x over previous
; #define LDSP(T, p) ((__attribute__((address_space(3))) T*)(p))
; DI int tidx() { int t = threadIdx.x; asm volatile("" : "+v"(t)); return t; }
; DI void gemm_issue_first(const bf16_t* __restrict__ A, int lda, const bf16_t* __restrict__ Bt, int ldb, int m0, int n0, char* smem) {
;   const int tid = tidx(), wave = tid >> 6, lane = tid & 63;
; #pragma unroll
;   for (int i = 0; i < 4; ++i) {
;     const int row = (i * 4 + wave) * 8 + (lane >> 3), chunk = (lane & 7) ^ ((row >> 1) & 7);
;     __builtin_amdgcn_global_load_lds((const unsigned*)(A + (size_t)(m0 + row) * lda + chunk * 8), LDSP(unsigned, smem + (i * 4 + wave) * 1024), 16, 0, 0);
;     __builtin_amdgcn_global_load_lds((const unsigned*)(Bt + (size_t)(n0 + row) * ldb + chunk * 8), LDSP(unsigned, smem + 16384 + (i * 4 + wave) * 1024), 16, 0, 0);
;   }
; }
; template <int EPI>
; DI void gemm_phase(const GArgs& g, char* smem) {
;     ...
;   if ((int)blockIdx.x < ntm * ntn) gemm_issue_first(g.A, g.lda, g.Bt, g.K, (blockIdx.x % ntm) * 128, (blockIdx.x / ntm) * 128, smem);
.LBB0_424:
	v_mov_b32_e32 v2, v190
	v_readlane_b32 s101, v253, 52
	s_cmpk_lt_u32 s101, 0x90
	s_cselect_b32 s101, 0, 0x80
	s_sub_u32 s100, s82, s101
	s_cmp_gt_u32 s100, 15
	s_cbranch_scc1 .LBB0_433
	v_mov_b32_e32 v3, v190
	v_readlane_b32 s3, v253, 8
	v_ashrrev_i32_e32 v6, 6, v3
	v_bfe_u32 v7, v3, 3, 3
	v_lshl_or_b32 v8, v6, 3, v7
	v_lshrrev_b32_e32 v0, 1, v8
	v_add_u32_e32 v4, s3, v8
	s_lshl_b64 s[0:1], s[80:81], 8
	v_readlane_b32 s2, v250, 60
	v_xor_b32_e32 v0, v0, v3
	v_ashrrev_i32_e32 v5, 31, v4
	v_readlane_b32 s4, v252, 61
	s_add_u32 s0, s2, s0
	v_readlane_b32 s2, v250, 61
	v_lshlrev_b64 v[4:5], 8, v[4:5]
	v_readlane_b32 s5, v252, 62
	v_lshlrev_b32_e32 v0, 4, v0
	v_lshlrev_b32_e32 v9, 10, v6
	s_addc_u32 s1, s2, s1
	v_lshl_add_u64 v[4:5], s[4:5], 0, v[4:5]
	v_and_b32_e32 v0, 0x70, v0
	v_readfirstlane_b32 s2, v9
	v_lshl_add_u64 v[4:5], v[4:5], 0, v[0:1]
	s_mov_b32 m0, s2
	s_mov_b32 s6, 0
	global_load_lds_dwordx4 v[4:5], off
	s_nop 0
	v_add_u32_e32 v4, s6, v8
	v_ashrrev_i32_e32 v5, 31, v4
	v_lshlrev_b64 v[4:5], 8, v[4:5]
	v_lshl_add_u64 v[4:5], s[0:1], 0, v[4:5]
	v_lshl_add_u64 v[4:5], v[4:5], 0, v[0:1]
	v_add_u32_e32 v0, 0x4000, v9
	v_add_u32_e32 v8, 4, v6
	v_readfirstlane_b32 s2, v0
	s_mov_b32 m0, s2
	v_lshl_or_b32 v9, v8, 3, v7
	global_load_lds_dwordx4 v[4:5], off
	v_lshrrev_b32_e32 v0, 1, v9
	v_add_u32_e32 v4, s3, v9
	v_xor_b32_e32 v0, v0, v3
	v_ashrrev_i32_e32 v5, 31, v4
	v_lshlrev_b64 v[4:5], 8, v[4:5]
	v_lshlrev_b32_e32 v0, 4, v0
	v_lshlrev_b32_e32 v8, 10, v8
	v_lshl_add_u64 v[4:5], s[4:5], 0, v[4:5]
	v_and_b32_e32 v0, 0x70, v0
	v_readfirstlane_b32 s2, v8
	v_lshl_add_u64 v[4:5], v[4:5], 0, v[0:1]
	s_mov_b32 m0, s2
	s_nop 0
	global_load_lds_dwordx4 v[4:5], off
	v_add_u32_e32 v4, s6, v9
	v_ashrrev_i32_e32 v5, 31, v4
	v_lshlrev_b64 v[4:5], 8, v[4:5]
	v_lshl_add_u64 v[4:5], s[0:1], 0, v[4:5]
	v_lshl_add_u64 v[4:5], v[4:5], 0, v[0:1]
	v_add_u32_e32 v0, 0x4000, v8
	v_add_u32_e32 v8, 8, v6
	v_readfirstlane_b32 s2, v0
	s_mov_b32 m0, s2
	v_lshl_or_b32 v9, v8, 3, v7
	global_load_lds_dwordx4 v[4:5], off
	v_lshrrev_b32_e32 v0, 1, v9
	v_add_u32_e32 v4, s3, v9
	v_xor_b32_e32 v0, v0, v3
	v_ashrrev_i32_e32 v5, 31, v4
	v_lshlrev_b64 v[4:5], 8, v[4:5]
	v_lshlrev_b32_e32 v0, 4, v0
	v_lshlrev_b32_e32 v8, 10, v8
	v_lshl_add_u64 v[4:5], s[4:5], 0, v[4:5]
	v_and_b32_e32 v0, 0x70, v0
	v_readfirstlane_b32 s2, v8
	v_lshl_add_u64 v[4:5], v[4:5], 0, v[0:1]
	s_mov_b32 m0, s2
	v_add_u32_e32 v6, 12, v6
	global_load_lds_dwordx4 v[4:5], off
	v_add_u32_e32 v4, s6, v9
	v_ashrrev_i32_e32 v5, 31, v4
	v_lshlrev_b64 v[4:5], 8, v[4:5]
	v_lshl_add_u64 v[4:5], s[0:1], 0, v[4:5]
	v_lshl_add_u64 v[4:5], v[4:5], 0, v[0:1]
	v_add_u32_e32 v0, 0x4000, v8
	v_lshl_or_b32 v7, v6, 3, v7
	v_readfirstlane_b32 s2, v0
	s_mov_b32 m0, s2
	v_lshrrev_b32_e32 v0, 1, v7
	global_load_lds_dwordx4 v[4:5], off
	v_add_u32_e32 v4, s3, v7
	v_xor_b32_e32 v0, v0, v3
	v_ashrrev_i32_e32 v5, 31, v4
	v_lshlrev_b64 v[4:5], 8, v[4:5]
	v_lshlrev_b32_e32 v0, 4, v0
	v_lshlrev_b32_e32 v3, 10, v6
	v_lshl_add_u64 v[4:5], s[4:5], 0, v[4:5]
	v_and_b32_e32 v0, 0x70, v0
	v_readfirstlane_b32 s2, v3
	v_lshl_add_u64 v[4:5], v[4:5], 0, v[0:1]
	s_mov_b32 m0, s2
	s_nop 0
	global_load_lds_dwordx4 v[4:5], off
	v_add_u32_e32 v4, s6, v7
	v_ashrrev_i32_e32 v5, 31, v4
	v_lshlrev_b64 v[4:5], 8, v[4:5]
	v_lshl_add_u64 v[4:5], s[0:1], 0, v[4:5]
	v_lshl_add_u64 v[4:5], v[4:5], 0, v[0:1]
	v_add_u32_e32 v0, 0x4000, v3
	v_and_b32_e32 v3, 15, v2
	v_readfirstlane_b32 s2, v0
	s_mov_b32 m0, s2
	v_ashrrev_i32_e32 v0, 1, v2
	global_load_lds_dwordx4 v[4:5], off
	s_movk_i32 s2, 0xffe0
	v_and_or_b32 v146, v0, s2, v3
	v_lshrrev_b32_e32 v0, 2, v2
	v_and_b32_e32 v147, 12, v0
	s_mov_b32 s6, s100
	s_branch .LBB0_427
